# down phase software-pipelined (gathers of item n+1 issued in halves while item n is consumed)
# speedup vs baseline: 1.1648x; 1.0069x over previous
; __device__ __forceinline__ void peer_down_phase(const Ctx& C, const unsigned char* ED, const bf16* HB, const float* RSS, float* SELG, const int* SELI) {
;     int gl = threadIdx.x & 63; asm volatile("" : "+v"(gl));
;     for (int wtile = C.gw; wtile < MTOK / 16; wtile += C.ngw) {
;         const int tok0 = wtile * 16;
;         int nvi0 = SELI[(size_t)tok0 * 128 + gl], nvi1 = SELI[(size_t)tok0 * 128 + 64 + gl]; float nvg0 = SELG[(size_t)tok0 * 128 + gl], nvg1 = SELG[(size_t)tok0 * 128 + 64 + gl];
;         v4u nh0 = __builtin_nontemporal_load((const v4u*)(HB + (size_t)tok0 * DM + 16 * gl)), nh1 = __builtin_nontemporal_load((const v4u*)(HB + (size_t)tok0 * DM + 16 * gl + 8));
;         float nrs = gl < 16 ? RSS[(size_t)tok0 * 16 + gl] : 0.f;
;         for (int ti = 0; ti < 16; ++ti) {
;             const size_t tok = (size_t)tok0 + ti;
;             const int vi0 = nvi0, vi1 = nvi1; const float vg0 = nvg0, vg1 = nvg1; const v4u h0 = nh0, h1 = nh1;
;             const float rstd_h = 1.0f / sqrtf(wave_sum(nrs) * (1.f / DM) + RMS_EPS);
;             if (ti + 1 < 16) { const size_t tn = tok + 1;
;                 nvi0 = SELI[tn * 128 + gl]; nvi1 = SELI[tn * 128 + 64 + gl]; nvg0 = SELG[tn * 128 + gl]; nvg1 = SELG[tn * 128 + 64 + gl];
;                 nh0 = __builtin_nontemporal_load((const v4u*)(HB + tn * DM + 16 * gl)); nh1 = __builtin_nontemporal_load((const v4u*)(HB + tn * DM + 16 * gl + 8));
;                 nrs = gl < 16 ? RSS[tn * 16 + gl] : 0.f; }
;             v2f hf[8];
; #pragma unroll
;             for (int w = 0; w < 4; ++w) { hf[w] = (v2f){bflo(h0[w]), bfhi(h0[w])}; hf[4 + w] = (v2f){bflo(h1[w]), bfhi(h1[w])}; }
;             v4u dnA[8], dnB[8]; int eidA[8], eidB[8];
; #pragma unroll
;             for (int k = 0; k < 8; ++k) { eidA[k] = __builtin_amdgcn_readlane(vi0, k); dnA[k] = *(const v4u*)(ED + (size_t)eidA[k] * DM + 16 * gl); }
; #pragma unroll
;             for (int k = 0; k < 8; ++k) { eidB[k] = __builtin_amdgcn_readlane(vi0, 8 + k); dnB[k] = *(const v4u*)(ED + (size_t)eidB[k] * DM + 16 * gl); }
.Ldn_new:
	v_readlane_b32 s0, v247, 53
	v_readlane_b32 s6, v249, 8
	v_readlane_b32 s7, v249, 9
	s_and_b32 s2, s0, 7
	s_lshl_b32 s40, s0, 5
	s_lshl_b32 s1, s2, 14
	s_lshl_b32 s41, s2, 10
	s_add_i32 s41, s41, 0x20000
	s_add_u32 s42, s6, 0x5600000
	s_addc_u32 s43, s7, 0
	s_add_u32 s44, s6, 0x2b600000
	s_addc_u32 s45, s7, 0
	s_add_u32 s6, s6, 0x2d600000
	s_addc_u32 s7, s7, 0
	v_and_b32_e32 v1, 7, v177
	v_lshlrev_b32_e32 v5, 5, v1
	v_lshlrev_b32_e32 v1, 4, v1
	v_lshrrev_b32_e32 v2, 3, v177
	v_lshl_add_u32 v2, v2, 2, s41
	v_lshlrev_b32_e32 v4, 2, v177
	v_add_u32_e32 v3, s41, v4
	v_add_u32_e32 v130, s1, v4
	v_lshlrev_b32_e32 v128, 4, v177
	v_add_u32_e32 v128, s1, v128
	v_mov_b32_e32 v132, 0
	v_mov_b32_e32 v133, 0
	v_mov_b32_e32 v134, 0
	v_mov_b32_e32 v135, 0
	ds_write_b128 v128, v[132:135]
	ds_write_b128 v128, v[132:135] offset:1024
	ds_write_b128 v128, v[132:135] offset:2048
	ds_write_b128 v128, v[132:135] offset:3072
	ds_write_b128 v128, v[132:135] offset:4096
	ds_write_b128 v128, v[132:135] offset:5120
	ds_write_b128 v128, v[132:135] offset:6144
	ds_write_b128 v128, v[132:135] offset:7168
	ds_write_b128 v128, v[132:135] offset:8192
	ds_write_b128 v128, v[132:135] offset:9216
	ds_write_b128 v128, v[132:135] offset:10240
	ds_write_b128 v128, v[132:135] offset:11264
	ds_write_b128 v128, v[132:135] offset:12288
	ds_write_b128 v128, v[132:135] offset:13312
	ds_write_b128 v128, v[132:135] offset:14336
	ds_write_b128 v128, v[132:135] offset:15360
	s_mov_b32 s46, 0x01010101
	s_mov_b32 s47, 0x01010101
	s_mov_b32 s38, 0
	s_mov_b32 s39, 0
	s_mov_b32 s10, 0
	s_lshr_b32 s0, s10, 5
	s_and_b32 s1, s10, 31
	s_add_i32 s1, s1, s40
	s_lshl_b32 s1, s1, 9
	s_add_u32 s12, s6, s1
	s_addc_u32 s13, s7, 0
	global_load_dword v6, v4, s[12:13]
	global_load_dword v7, v4, s[12:13] offset:256
	s_waitcnt vmcnt(0)
	v_add_u32_e32 v105, s39, v3
	ds_write_b32 v105, v6
	ds_write_b32 v105, v7 offset:256
	s_mov_b32 s10, 1
	s_lshr_b32 s0, s10, 5
	s_and_b32 s1, s10, 31
	s_add_i32 s1, s1, s40
	s_lshl_b32 s1, s1, 9
	s_add_u32 s12, s6, s1
	s_addc_u32 s13, s7, 0
	global_load_dword v6, v4, s[12:13]
	global_load_dword v7, v4, s[12:13] offset:256
	s_waitcnt vmcnt(0)
	s_movk_i32 s11, 0x200
	v_add_u32_e32 v105, s11, v3
	ds_write_b32 v105, v6
	ds_write_b32 v105, v7 offset:256
	s_mov_b32 s10, 0
	s_lshr_b32 s0, s10, 5
	s_and_b32 s1, s10, 31
	s_add_i32 s1, s1, s40
	s_lshl_b32 s1, s1, 11
	s_lshl_b32 s0, s0, 8
	s_add_u32 s14, s60, s0
	s_addc_u32 s15, s61, 0
	s_add_u32 s14, s14, s1
	s_addc_u32 s15, s15, 0
	global_load_dwordx4 v[8:11], v5, s[14:15]
	global_load_dwordx4 v[12:15], v5, s[14:15] offset:16
	v_add_u32_e32 v106, s39, v2
	ds_read_b32 v32, v106
	ds_read_b32 v33, v106 offset:32
	ds_read_b32 v34, v106 offset:64
	ds_read_b32 v35, v106 offset:96
	ds_read_b32 v36, v106 offset:128
	ds_read_b32 v37, v106 offset:160
	ds_read_b32 v38, v106 offset:192
	ds_read_b32 v39, v106 offset:224
	v_add_u32_e32 v106, s39, v2
	ds_read_b32 v40, v106 offset:256
	ds_read_b32 v41, v106 offset:288
	ds_read_b32 v42, v106 offset:320
	ds_read_b32 v43, v106 offset:352
	ds_read_b32 v44, v106 offset:384
	ds_read_b32 v45, v106 offset:416
	ds_read_b32 v46, v106 offset:448
	ds_read_b32 v47, v106 offset:480
	s_lshr_b32 s0, s10, 5
	s_and_b32 s1, s10, 31
	s_add_i32 s1, s1, s40
	s_lshl_b32 s0, s0, 21
	s_add_u32 s8, s42, s0
	s_addc_u32 s9, s43, 0
	s_waitcnt lgkmcnt(4)
	v_lshl_add_u32 v32, v32, 7, v1
	global_load_dwordx4 v[48:51], v32, s[8:9]
	v_lshl_add_u32 v33, v33, 7, v1
	global_load_dwordx4 v[52:55], v33, s[8:9]
	v_lshl_add_u32 v34, v34, 7, v1
	global_load_dwordx4 v[56:59], v34, s[8:9]
	v_lshl_add_u32 v35, v35, 7, v1
	global_load_dwordx4 v[60:63], v35, s[8:9]
	s_waitcnt lgkmcnt(0)
	v_lshl_add_u32 v36, v36, 7, v1
	global_load_dwordx4 v[64:67], v36, s[8:9]
	v_lshl_add_u32 v37, v37, 7, v1
	global_load_dwordx4 v[68:71], v37, s[8:9]
	v_lshl_add_u32 v38, v38, 7, v1
	global_load_dwordx4 v[72:75], v38, s[8:9]
	v_lshl_add_u32 v39, v39, 7, v1
	global_load_dwordx4 v[76:79], v39, s[8:9]
	s_lshr_b32 s0, s10, 5
	s_and_b32 s1, s10, 31
	s_add_i32 s1, s1, s40
	s_lshl_b32 s0, s0, 21
	s_add_u32 s8, s42, s0
	s_addc_u32 s9, s43, 0
	s_waitcnt lgkmcnt(4)
	v_lshl_add_u32 v40, v40, 7, v1
	global_load_dwordx4 v[80:83], v40, s[8:9]
	v_lshl_add_u32 v41, v41, 7, v1
	global_load_dwordx4 v[84:87], v41, s[8:9]
	v_lshl_add_u32 v42, v42, 7, v1
	global_load_dwordx4 v[88:91], v42, s[8:9]
	v_lshl_add_u32 v43, v43, 7, v1
	global_load_dwordx4 v[92:95], v43, s[8:9]
	s_waitcnt lgkmcnt(0)
	v_lshl_add_u32 v44, v44, 7, v1
	global_load_dwordx4 v[96:99], v44, s[8:9]
	v_lshl_add_u32 v45, v45, 7, v1
	global_load_dwordx4 v[100:103], v45, s[8:9]
	v_lshl_add_u32 v46, v46, 7, v1
	global_load_dwordx4 v[108:111], v46, s[8:9]
	v_lshl_add_u32 v47, v47, 7, v1
	global_load_dwordx4 v[112:115], v47, s[8:9]
	s_mov_b32 s10, 2
	s_lshr_b32 s0, s10, 5
	s_and_b32 s1, s10, 31
	s_add_i32 s1, s1, s40
	s_lshl_b32 s1, s1, 9
	s_add_u32 s12, s6, s1
	s_addc_u32 s13, s7, 0
	global_load_dword v6, v4, s[12:13]
	global_load_dword v7, v4, s[12:13] offset:256
; __device__ __forceinline__ float dot16_fp8(v4u a, const v2f (&h)[8]) {
;     v2f acc = (v2f){0.f, 0.f};
; #pragma unroll
;     for (int w = 0; w < 4; ++w) { const int wd = (int)a[w]; const v2f lo = __builtin_amdgcn_cvt_pk_f32_fp8(wd, false), hi = __builtin_amdgcn_cvt_pk_f32_fp8(wd, true);
;         acc = lo * h[2 * w] + acc; acc = hi * h[2 * w + 1] + acc; }
;     return acc.x + acc.y;
; }
; __device__ __forceinline__ void peer_down_phase(const Ctx& C, const unsigned char* ED, const bf16* HB, const float* RSS, float* SELG, const int* SELI) {
;     ...
;             v2f hf[8];
; #pragma unroll
;             for (int w = 0; w < 4; ++w) { hf[w] = (v2f){bflo(h0[w]), bfhi(h0[w])}; hf[4 + w] = (v2f){bflo(h1[w]), bfhi(h1[w])}; }
;             v4u dnA[8], dnB[8]; int eidA[8], eidB[8];
; #pragma unroll
;             for (int k = 0; k < 8; ++k) { eidA[k] = __builtin_amdgcn_readlane(vi0, k); dnA[k] = *(const v4u*)(ED + (size_t)eidA[k] * DM + 16 * gl); }
; #pragma unroll
;             for (int k = 0; k < 8; ++k) { eidB[k] = __builtin_amdgcn_readlane(vi0, 8 + k); dnB[k] = *(const v4u*)(ED + (size_t)eidB[k] * DM + 16 * gl); }
.Ldnp_item:
	s_waitcnt vmcnt(18)
	v_lshlrev_b32_e32 v16, 16, v8
	v_and_b32_e32 v17, 0xffff0000, v8
	v_lshlrev_b32_e32 v18, 16, v9
	v_and_b32_e32 v19, 0xffff0000, v9
	v_lshlrev_b32_e32 v20, 16, v10
	v_and_b32_e32 v21, 0xffff0000, v10
	v_lshlrev_b32_e32 v22, 16, v11
	v_and_b32_e32 v23, 0xffff0000, v11
	v_lshlrev_b32_e32 v24, 16, v12
	v_and_b32_e32 v25, 0xffff0000, v12
	v_lshlrev_b32_e32 v26, 16, v13
	v_and_b32_e32 v27, 0xffff0000, v13
	v_lshlrev_b32_e32 v28, 16, v14
	v_and_b32_e32 v29, 0xffff0000, v14
	v_lshlrev_b32_e32 v30, 16, v15
	v_and_b32_e32 v31, 0xffff0000, v15
	s_add_i32 s10, s38, 1
	s_min_u32 s10, s10, 0xff
	s_lshr_b32 s0, s10, 5
	s_and_b32 s1, s10, 31
	s_add_i32 s1, s1, s40
	s_lshl_b32 s1, s1, 11
	s_lshl_b32 s0, s0, 8
	s_add_u32 s14, s60, s0
	s_addc_u32 s15, s61, 0
	s_add_u32 s14, s14, s1
	s_addc_u32 s15, s15, 0
	global_load_dwordx4 v[8:11], v5, s[14:15]
	global_load_dwordx4 v[12:15], v5, s[14:15] offset:16
	s_xor_b32 s11, s39, 0x200
	s_waitcnt vmcnt(19)
	v_cvt_pk_f32_fp8_e32 v[142:143], v48
	v_cvt_pk_f32_fp8_sdwa v[144:145], v48 src0_sel:WORD_1
	v_cvt_pk_f32_fp8_e32 v[146:147], v49
	v_cvt_pk_f32_fp8_sdwa v[148:149], v49 src0_sel:WORD_1
	v_cvt_pk_f32_fp8_e32 v[150:151], v50
	v_cvt_pk_f32_fp8_sdwa v[152:153], v50 src0_sel:WORD_1
	v_cvt_pk_f32_fp8_e32 v[154:155], v51
	v_cvt_pk_f32_fp8_sdwa v[156:157], v51 src0_sel:WORD_1
	v_pk_mul_f32 v[124:125], v[142:143], v[16:17]
	v_pk_mul_f32 v[126:127], v[144:145], v[18:19]
	v_pk_fma_f32 v[124:125], v[146:147], v[20:21], v[124:125]
	v_pk_fma_f32 v[126:127], v[148:149], v[22:23], v[126:127]
	v_pk_fma_f32 v[124:125], v[150:151], v[24:25], v[124:125]
	v_pk_fma_f32 v[126:127], v[152:153], v[26:27], v[126:127]
	v_pk_fma_f32 v[124:125], v[154:155], v[28:29], v[124:125]
	v_pk_fma_f32 v[126:127], v[156:157], v[30:31], v[126:127]
	v_pk_add_f32 v[124:125], v[124:125], v[126:127]
	v_add_f32_e32 v116, v124, v125
	s_waitcnt vmcnt(18)
	v_cvt_pk_f32_fp8_e32 v[142:143], v52
	v_cvt_pk_f32_fp8_sdwa v[144:145], v52 src0_sel:WORD_1
	v_cvt_pk_f32_fp8_e32 v[146:147], v53
	v_cvt_pk_f32_fp8_sdwa v[148:149], v53 src0_sel:WORD_1
	v_cvt_pk_f32_fp8_e32 v[150:151], v54
	v_cvt_pk_f32_fp8_sdwa v[152:153], v54 src0_sel:WORD_1
	v_cvt_pk_f32_fp8_e32 v[154:155], v55
	v_cvt_pk_f32_fp8_sdwa v[156:157], v55 src0_sel:WORD_1
	v_pk_mul_f32 v[124:125], v[142:143], v[16:17]
	v_pk_mul_f32 v[126:127], v[144:145], v[18:19]
	v_pk_fma_f32 v[124:125], v[146:147], v[20:21], v[124:125]
	v_pk_fma_f32 v[126:127], v[148:149], v[22:23], v[126:127]
	v_pk_fma_f32 v[124:125], v[150:151], v[24:25], v[124:125]
	v_pk_fma_f32 v[126:127], v[152:153], v[26:27], v[126:127]
	v_pk_fma_f32 v[124:125], v[154:155], v[28:29], v[124:125]
	v_pk_fma_f32 v[126:127], v[156:157], v[30:31], v[126:127]
	v_pk_add_f32 v[124:125], v[124:125], v[126:127]
	v_add_f32_e32 v117, v124, v125
	s_waitcnt vmcnt(17)
	v_cvt_pk_f32_fp8_e32 v[142:143], v56
	v_cvt_pk_f32_fp8_sdwa v[144:145], v56 src0_sel:WORD_1
	v_cvt_pk_f32_fp8_e32 v[146:147], v57
	v_cvt_pk_f32_fp8_sdwa v[148:149], v57 src0_sel:WORD_1
	v_cvt_pk_f32_fp8_e32 v[150:151], v58
	v_cvt_pk_f32_fp8_sdwa v[152:153], v58 src0_sel:WORD_1
	v_cvt_pk_f32_fp8_e32 v[154:155], v59
	v_cvt_pk_f32_fp8_sdwa v[156:157], v59 src0_sel:WORD_1
	v_pk_mul_f32 v[124:125], v[142:143], v[16:17]
	v_pk_mul_f32 v[126:127], v[144:145], v[18:19]
	v_pk_fma_f32 v[124:125], v[146:147], v[20:21], v[124:125]
	v_pk_fma_f32 v[126:127], v[148:149], v[22:23], v[126:127]
	v_pk_fma_f32 v[124:125], v[150:151], v[24:25], v[124:125]
	v_pk_fma_f32 v[126:127], v[152:153], v[26:27], v[126:127]
	v_pk_fma_f32 v[124:125], v[154:155], v[28:29], v[124:125]
	v_pk_fma_f32 v[126:127], v[156:157], v[30:31], v[126:127]
	v_pk_add_f32 v[124:125], v[124:125], v[126:127]
	v_add_f32_e32 v118, v124, v125
	s_waitcnt vmcnt(16)
	v_cvt_pk_f32_fp8_e32 v[142:143], v60
	v_cvt_pk_f32_fp8_sdwa v[144:145], v60 src0_sel:WORD_1
	v_cvt_pk_f32_fp8_e32 v[146:147], v61
	v_cvt_pk_f32_fp8_sdwa v[148:149], v61 src0_sel:WORD_1
	v_cvt_pk_f32_fp8_e32 v[150:151], v62
	v_cvt_pk_f32_fp8_sdwa v[152:153], v62 src0_sel:WORD_1
	v_cvt_pk_f32_fp8_e32 v[154:155], v63
	v_cvt_pk_f32_fp8_sdwa v[156:157], v63 src0_sel:WORD_1
	v_pk_mul_f32 v[124:125], v[142:143], v[16:17]
	v_pk_mul_f32 v[126:127], v[144:145], v[18:19]
	v_pk_fma_f32 v[124:125], v[146:147], v[20:21], v[124:125]
	v_pk_fma_f32 v[126:127], v[148:149], v[22:23], v[126:127]
	v_pk_fma_f32 v[124:125], v[150:151], v[24:25], v[124:125]
	v_pk_fma_f32 v[126:127], v[152:153], v[26:27], v[126:127]
	v_pk_fma_f32 v[124:125], v[154:155], v[28:29], v[124:125]
	v_pk_fma_f32 v[126:127], v[156:157], v[30:31], v[126:127]
	v_pk_add_f32 v[124:125], v[124:125], v[126:127]
	v_add_f32_e32 v119, v124, v125
	s_waitcnt vmcnt(15)
	v_cvt_pk_f32_fp8_e32 v[142:143], v64
	v_cvt_pk_f32_fp8_sdwa v[144:145], v64 src0_sel:WORD_1
	v_cvt_pk_f32_fp8_e32 v[146:147], v65
	v_cvt_pk_f32_fp8_sdwa v[148:149], v65 src0_sel:WORD_1
	v_cvt_pk_f32_fp8_e32 v[150:151], v66
	v_cvt_pk_f32_fp8_sdwa v[152:153], v66 src0_sel:WORD_1
	v_cvt_pk_f32_fp8_e32 v[154:155], v67
	v_cvt_pk_f32_fp8_sdwa v[156:157], v67 src0_sel:WORD_1
	v_pk_mul_f32 v[124:125], v[142:143], v[16:17]
	v_pk_mul_f32 v[126:127], v[144:145], v[18:19]
	v_pk_fma_f32 v[124:125], v[146:147], v[20:21], v[124:125]
	v_pk_fma_f32 v[126:127], v[148:149], v[22:23], v[126:127]
	v_pk_fma_f32 v[124:125], v[150:151], v[24:25], v[124:125]
	v_pk_fma_f32 v[126:127], v[152:153], v[26:27], v[126:127]
	v_pk_fma_f32 v[124:125], v[154:155], v[28:29], v[124:125]
	v_pk_fma_f32 v[126:127], v[156:157], v[30:31], v[126:127]
	v_pk_add_f32 v[124:125], v[124:125], v[126:127]
	v_add_f32_e32 v120, v124, v125
	s_waitcnt vmcnt(14)
	v_cvt_pk_f32_fp8_e32 v[142:143], v68
	v_cvt_pk_f32_fp8_sdwa v[144:145], v68 src0_sel:WORD_1
	v_cvt_pk_f32_fp8_e32 v[146:147], v69
	v_cvt_pk_f32_fp8_sdwa v[148:149], v69 src0_sel:WORD_1
	v_cvt_pk_f32_fp8_e32 v[150:151], v70
	v_cvt_pk_f32_fp8_sdwa v[152:153], v70 src0_sel:WORD_1
	v_cvt_pk_f32_fp8_e32 v[154:155], v71
	v_cvt_pk_f32_fp8_sdwa v[156:157], v71 src0_sel:WORD_1
	v_pk_mul_f32 v[124:125], v[142:143], v[16:17]
	v_pk_mul_f32 v[126:127], v[144:145], v[18:19]
	v_pk_fma_f32 v[124:125], v[146:147], v[20:21], v[124:125]
	v_pk_fma_f32 v[126:127], v[148:149], v[22:23], v[126:127]
	v_pk_fma_f32 v[124:125], v[150:151], v[24:25], v[124:125]
	v_pk_fma_f32 v[126:127], v[152:153], v[26:27], v[126:127]
	v_pk_fma_f32 v[124:125], v[154:155], v[28:29], v[124:125]
	v_pk_fma_f32 v[126:127], v[156:157], v[30:31], v[126:127]
	v_pk_add_f32 v[124:125], v[124:125], v[126:127]
	v_add_f32_e32 v121, v124, v125
	s_waitcnt vmcnt(13)
	v_cvt_pk_f32_fp8_e32 v[142:143], v72
	v_cvt_pk_f32_fp8_sdwa v[144:145], v72 src0_sel:WORD_1
	v_cvt_pk_f32_fp8_e32 v[146:147], v73
	v_cvt_pk_f32_fp8_sdwa v[148:149], v73 src0_sel:WORD_1
	v_cvt_pk_f32_fp8_e32 v[150:151], v74
	v_cvt_pk_f32_fp8_sdwa v[152:153], v74 src0_sel:WORD_1
	v_cvt_pk_f32_fp8_e32 v[154:155], v75
	v_cvt_pk_f32_fp8_sdwa v[156:157], v75 src0_sel:WORD_1
	v_pk_mul_f32 v[124:125], v[142:143], v[16:17]
	v_pk_mul_f32 v[126:127], v[144:145], v[18:19]
	v_pk_fma_f32 v[124:125], v[146:147], v[20:21], v[124:125]
	v_pk_fma_f32 v[126:127], v[148:149], v[22:23], v[126:127]
	v_pk_fma_f32 v[124:125], v[150:151], v[24:25], v[124:125]
	v_pk_fma_f32 v[126:127], v[152:153], v[26:27], v[126:127]
	v_pk_fma_f32 v[124:125], v[154:155], v[28:29], v[124:125]
	v_pk_fma_f32 v[126:127], v[156:157], v[30:31], v[126:127]
	v_pk_add_f32 v[124:125], v[124:125], v[126:127]
	v_add_f32_e32 v122, v124, v125
	s_waitcnt vmcnt(12)
	v_cvt_pk_f32_fp8_e32 v[142:143], v76
	v_cvt_pk_f32_fp8_sdwa v[144:145], v76 src0_sel:WORD_1
	v_cvt_pk_f32_fp8_e32 v[146:147], v77
	v_cvt_pk_f32_fp8_sdwa v[148:149], v77 src0_sel:WORD_1
	v_cvt_pk_f32_fp8_e32 v[150:151], v78
	v_cvt_pk_f32_fp8_sdwa v[152:153], v78 src0_sel:WORD_1
	v_cvt_pk_f32_fp8_e32 v[154:155], v79
	v_cvt_pk_f32_fp8_sdwa v[156:157], v79 src0_sel:WORD_1
	v_pk_mul_f32 v[124:125], v[142:143], v[16:17]
	v_pk_mul_f32 v[126:127], v[144:145], v[18:19]
	v_pk_fma_f32 v[124:125], v[146:147], v[20:21], v[124:125]
	v_pk_fma_f32 v[126:127], v[148:149], v[22:23], v[126:127]
	v_pk_fma_f32 v[124:125], v[150:151], v[24:25], v[124:125]
	v_pk_fma_f32 v[126:127], v[152:153], v[26:27], v[126:127]
	v_pk_fma_f32 v[124:125], v[154:155], v[28:29], v[124:125]
	v_pk_fma_f32 v[126:127], v[156:157], v[30:31], v[126:127]
	v_pk_add_f32 v[124:125], v[124:125], v[126:127]
	v_add_f32_e32 v123, v124, v125
	v_add_u32_e32 v106, s11, v2
	ds_read_b32 v32, v106
	ds_read_b32 v33, v106 offset:32
	ds_read_b32 v34, v106 offset:64
	ds_read_b32 v35, v106 offset:96
	ds_read_b32 v36, v106 offset:128
	ds_read_b32 v37, v106 offset:160
	ds_read_b32 v38, v106 offset:192
	ds_read_b32 v39, v106 offset:224
	s_lshr_b32 s0, s10, 5
	s_and_b32 s1, s10, 31
	s_add_i32 s1, s1, s40
	s_lshl_b32 s0, s0, 21
	s_add_u32 s8, s42, s0
	s_addc_u32 s9, s43, 0
	s_waitcnt lgkmcnt(4)
	v_lshl_add_u32 v32, v32, 7, v1
	global_load_dwordx4 v[48:51], v32, s[8:9]
	v_lshl_add_u32 v33, v33, 7, v1
	global_load_dwordx4 v[52:55], v33, s[8:9]
	v_lshl_add_u32 v34, v34, 7, v1
	global_load_dwordx4 v[56:59], v34, s[8:9]
	v_lshl_add_u32 v35, v35, 7, v1
	global_load_dwordx4 v[60:63], v35, s[8:9]
	s_waitcnt lgkmcnt(0)
	v_lshl_add_u32 v36, v36, 7, v1
	global_load_dwordx4 v[64:67], v36, s[8:9]
	v_lshl_add_u32 v37, v37, 7, v1
	global_load_dwordx4 v[68:71], v37, s[8:9]
	v_lshl_add_u32 v38, v38, 7, v1
	global_load_dwordx4 v[72:75], v38, s[8:9]
	v_lshl_add_u32 v39, v39, 7, v1
	global_load_dwordx4 v[76:79], v39, s[8:9]
	s_nop 1
	v_add_f32_dpp v116, v116, v116 quad_perm:[1,0,3,2] row_mask:0xf bank_mask:0xf
	v_add_f32_dpp v117, v117, v117 quad_perm:[1,0,3,2] row_mask:0xf bank_mask:0xf
	v_add_f32_dpp v118, v118, v118 quad_perm:[1,0,3,2] row_mask:0xf bank_mask:0xf
	v_add_f32_dpp v119, v119, v119 quad_perm:[1,0,3,2] row_mask:0xf bank_mask:0xf
	v_add_f32_dpp v120, v120, v120 quad_perm:[1,0,3,2] row_mask:0xf bank_mask:0xf
	v_add_f32_dpp v121, v121, v121 quad_perm:[1,0,3,2] row_mask:0xf bank_mask:0xf
	v_add_f32_dpp v122, v122, v122 quad_perm:[1,0,3,2] row_mask:0xf bank_mask:0xf
	v_add_f32_dpp v123, v123, v123 quad_perm:[1,0,3,2] row_mask:0xf bank_mask:0xf
	v_add_f32_dpp v116, v116, v116 quad_perm:[2,3,0,1] row_mask:0xf bank_mask:0xf
	v_add_f32_dpp v117, v117, v117 quad_perm:[2,3,0,1] row_mask:0xf bank_mask:0xf
	v_add_f32_dpp v118, v118, v118 quad_perm:[2,3,0,1] row_mask:0xf bank_mask:0xf
	v_add_f32_dpp v119, v119, v119 quad_perm:[2,3,0,1] row_mask:0xf bank_mask:0xf
	v_add_f32_dpp v120, v120, v120 quad_perm:[2,3,0,1] row_mask:0xf bank_mask:0xf
	v_add_f32_dpp v121, v121, v121 quad_perm:[2,3,0,1] row_mask:0xf bank_mask:0xf
	v_add_f32_dpp v122, v122, v122 quad_perm:[2,3,0,1] row_mask:0xf bank_mask:0xf
	v_add_f32_dpp v123, v123, v123 quad_perm:[2,3,0,1] row_mask:0xf bank_mask:0xf
	v_add_f32_dpp v116, v116, v116 row_half_mirror row_mask:0xf bank_mask:0xf
	v_add_f32_dpp v117, v117, v117 row_half_mirror row_mask:0xf bank_mask:0xf
	v_add_f32_dpp v118, v118, v118 row_half_mirror row_mask:0xf bank_mask:0xf
	v_add_f32_dpp v119, v119, v119 row_half_mirror row_mask:0xf bank_mask:0xf
	v_add_f32_dpp v120, v120, v120 row_half_mirror row_mask:0xf bank_mask:0xf
	v_add_f32_dpp v121, v121, v121 row_half_mirror row_mask:0xf bank_mask:0xf
	v_add_f32_dpp v122, v122, v122 row_half_mirror row_mask:0xf bank_mask:0xf
	v_add_f32_dpp v123, v123, v123 row_half_mirror row_mask:0xf bank_mask:0xf
	v_mov_b32_e32 v129, v116
	s_lshl_b64 s[0:1], s[46:47], 1
	v_cndmask_b32_e64 v129, v129, v117, s[0:1]
	s_lshl_b64 s[0:1], s[46:47], 2
	v_cndmask_b32_e64 v129, v129, v118, s[0:1]
	s_lshl_b64 s[0:1], s[46:47], 3
	v_cndmask_b32_e64 v129, v129, v119, s[0:1]
	s_lshl_b64 s[0:1], s[46:47], 4
	v_cndmask_b32_e64 v129, v129, v120, s[0:1]
	s_lshl_b64 s[0:1], s[46:47], 5
	v_cndmask_b32_e64 v129, v129, v121, s[0:1]
	s_lshl_b64 s[0:1], s[46:47], 6
	v_cndmask_b32_e64 v129, v129, v122, s[0:1]
	s_lshl_b64 s[0:1], s[46:47], 7
	v_cndmask_b32_e64 v129, v129, v123, s[0:1]
	s_waitcnt vmcnt(19)
; __device__ __forceinline__ float dot16_fp8(v4u a, const v2f (&h)[8]) {
;     v2f acc = (v2f){0.f, 0.f};
; #pragma unroll
;     for (int w = 0; w < 4; ++w) { const int wd = (int)a[w]; const v2f lo = __builtin_amdgcn_cvt_pk_f32_fp8(wd, false), hi = __builtin_amdgcn_cvt_pk_f32_fp8(wd, true);
;         acc = lo * h[2 * w] + acc; acc = hi * h[2 * w + 1] + acc; }
;     return acc.x + acc.y;
; }
	v_cvt_pk_f32_fp8_e32 v[142:143], v80
	v_cvt_pk_f32_fp8_sdwa v[144:145], v80 src0_sel:WORD_1
	v_cvt_pk_f32_fp8_e32 v[146:147], v81
	v_cvt_pk_f32_fp8_sdwa v[148:149], v81 src0_sel:WORD_1
	v_cvt_pk_f32_fp8_e32 v[150:151], v82
	v_cvt_pk_f32_fp8_sdwa v[152:153], v82 src0_sel:WORD_1
	v_cvt_pk_f32_fp8_e32 v[154:155], v83
	v_cvt_pk_f32_fp8_sdwa v[156:157], v83 src0_sel:WORD_1
	v_pk_mul_f32 v[124:125], v[142:143], v[16:17]
	v_pk_mul_f32 v[126:127], v[144:145], v[18:19]
	v_pk_fma_f32 v[124:125], v[146:147], v[20:21], v[124:125]
	v_pk_fma_f32 v[126:127], v[148:149], v[22:23], v[126:127]
	v_pk_fma_f32 v[124:125], v[150:151], v[24:25], v[124:125]
	v_pk_fma_f32 v[126:127], v[152:153], v[26:27], v[126:127]
	v_pk_fma_f32 v[124:125], v[154:155], v[28:29], v[124:125]
	v_pk_fma_f32 v[126:127], v[156:157], v[30:31], v[126:127]
	v_pk_add_f32 v[124:125], v[124:125], v[126:127]
	v_add_f32_e32 v116, v124, v125
	s_waitcnt vmcnt(18)
	v_cvt_pk_f32_fp8_e32 v[142:143], v84
	v_cvt_pk_f32_fp8_sdwa v[144:145], v84 src0_sel:WORD_1
	v_cvt_pk_f32_fp8_e32 v[146:147], v85
	v_cvt_pk_f32_fp8_sdwa v[148:149], v85 src0_sel:WORD_1
	v_cvt_pk_f32_fp8_e32 v[150:151], v86
	v_cvt_pk_f32_fp8_sdwa v[152:153], v86 src0_sel:WORD_1
	v_cvt_pk_f32_fp8_e32 v[154:155], v87
	v_cvt_pk_f32_fp8_sdwa v[156:157], v87 src0_sel:WORD_1
	v_pk_mul_f32 v[124:125], v[142:143], v[16:17]
	v_pk_mul_f32 v[126:127], v[144:145], v[18:19]
	v_pk_fma_f32 v[124:125], v[146:147], v[20:21], v[124:125]
	v_pk_fma_f32 v[126:127], v[148:149], v[22:23], v[126:127]
	v_pk_fma_f32 v[124:125], v[150:151], v[24:25], v[124:125]
	v_pk_fma_f32 v[126:127], v[152:153], v[26:27], v[126:127]
	v_pk_fma_f32 v[124:125], v[154:155], v[28:29], v[124:125]
	v_pk_fma_f32 v[126:127], v[156:157], v[30:31], v[126:127]
	v_pk_add_f32 v[124:125], v[124:125], v[126:127]
	v_add_f32_e32 v117, v124, v125
	s_waitcnt vmcnt(17)
	v_cvt_pk_f32_fp8_e32 v[142:143], v88
	v_cvt_pk_f32_fp8_sdwa v[144:145], v88 src0_sel:WORD_1
	v_cvt_pk_f32_fp8_e32 v[146:147], v89
	v_cvt_pk_f32_fp8_sdwa v[148:149], v89 src0_sel:WORD_1
	v_cvt_pk_f32_fp8_e32 v[150:151], v90
	v_cvt_pk_f32_fp8_sdwa v[152:153], v90 src0_sel:WORD_1
	v_cvt_pk_f32_fp8_e32 v[154:155], v91
	v_cvt_pk_f32_fp8_sdwa v[156:157], v91 src0_sel:WORD_1
	v_pk_mul_f32 v[124:125], v[142:143], v[16:17]
	v_pk_mul_f32 v[126:127], v[144:145], v[18:19]
	v_pk_fma_f32 v[124:125], v[146:147], v[20:21], v[124:125]
	v_pk_fma_f32 v[126:127], v[148:149], v[22:23], v[126:127]
	v_pk_fma_f32 v[124:125], v[150:151], v[24:25], v[124:125]
	v_pk_fma_f32 v[126:127], v[152:153], v[26:27], v[126:127]
	v_pk_fma_f32 v[124:125], v[154:155], v[28:29], v[124:125]
	v_pk_fma_f32 v[126:127], v[156:157], v[30:31], v[126:127]
	v_pk_add_f32 v[124:125], v[124:125], v[126:127]
	v_add_f32_e32 v118, v124, v125
	s_waitcnt vmcnt(16)
	v_cvt_pk_f32_fp8_e32 v[142:143], v92
	v_cvt_pk_f32_fp8_sdwa v[144:145], v92 src0_sel:WORD_1
	v_cvt_pk_f32_fp8_e32 v[146:147], v93
	v_cvt_pk_f32_fp8_sdwa v[148:149], v93 src0_sel:WORD_1
	v_cvt_pk_f32_fp8_e32 v[150:151], v94
	v_cvt_pk_f32_fp8_sdwa v[152:153], v94 src0_sel:WORD_1
	v_cvt_pk_f32_fp8_e32 v[154:155], v95
	v_cvt_pk_f32_fp8_sdwa v[156:157], v95 src0_sel:WORD_1
	v_pk_mul_f32 v[124:125], v[142:143], v[16:17]
	v_pk_mul_f32 v[126:127], v[144:145], v[18:19]
	v_pk_fma_f32 v[124:125], v[146:147], v[20:21], v[124:125]
	v_pk_fma_f32 v[126:127], v[148:149], v[22:23], v[126:127]
	v_pk_fma_f32 v[124:125], v[150:151], v[24:25], v[124:125]
	v_pk_fma_f32 v[126:127], v[152:153], v[26:27], v[126:127]
	v_pk_fma_f32 v[124:125], v[154:155], v[28:29], v[124:125]
	v_pk_fma_f32 v[126:127], v[156:157], v[30:31], v[126:127]
	v_pk_add_f32 v[124:125], v[124:125], v[126:127]
	v_add_f32_e32 v119, v124, v125
	s_waitcnt vmcnt(15)
	v_cvt_pk_f32_fp8_e32 v[142:143], v96
	v_cvt_pk_f32_fp8_sdwa v[144:145], v96 src0_sel:WORD_1
	v_cvt_pk_f32_fp8_e32 v[146:147], v97
	v_cvt_pk_f32_fp8_sdwa v[148:149], v97 src0_sel:WORD_1
	v_cvt_pk_f32_fp8_e32 v[150:151], v98
	v_cvt_pk_f32_fp8_sdwa v[152:153], v98 src0_sel:WORD_1
	v_cvt_pk_f32_fp8_e32 v[154:155], v99
	v_cvt_pk_f32_fp8_sdwa v[156:157], v99 src0_sel:WORD_1
	v_pk_mul_f32 v[124:125], v[142:143], v[16:17]
	v_pk_mul_f32 v[126:127], v[144:145], v[18:19]
	v_pk_fma_f32 v[124:125], v[146:147], v[20:21], v[124:125]
	v_pk_fma_f32 v[126:127], v[148:149], v[22:23], v[126:127]
	v_pk_fma_f32 v[124:125], v[150:151], v[24:25], v[124:125]
	v_pk_fma_f32 v[126:127], v[152:153], v[26:27], v[126:127]
	v_pk_fma_f32 v[124:125], v[154:155], v[28:29], v[124:125]
	v_pk_fma_f32 v[126:127], v[156:157], v[30:31], v[126:127]
	v_pk_add_f32 v[124:125], v[124:125], v[126:127]
	v_add_f32_e32 v120, v124, v125
	s_waitcnt vmcnt(14)
	v_cvt_pk_f32_fp8_e32 v[142:143], v100
	v_cvt_pk_f32_fp8_sdwa v[144:145], v100 src0_sel:WORD_1
	v_cvt_pk_f32_fp8_e32 v[146:147], v101
	v_cvt_pk_f32_fp8_sdwa v[148:149], v101 src0_sel:WORD_1
	v_cvt_pk_f32_fp8_e32 v[150:151], v102
	v_cvt_pk_f32_fp8_sdwa v[152:153], v102 src0_sel:WORD_1
	v_cvt_pk_f32_fp8_e32 v[154:155], v103
	v_cvt_pk_f32_fp8_sdwa v[156:157], v103 src0_sel:WORD_1
	v_pk_mul_f32 v[124:125], v[142:143], v[16:17]
	v_pk_mul_f32 v[126:127], v[144:145], v[18:19]
	v_pk_fma_f32 v[124:125], v[146:147], v[20:21], v[124:125]
	v_pk_fma_f32 v[126:127], v[148:149], v[22:23], v[126:127]
	v_pk_fma_f32 v[124:125], v[150:151], v[24:25], v[124:125]
	v_pk_fma_f32 v[126:127], v[152:153], v[26:27], v[126:127]
	v_pk_fma_f32 v[124:125], v[154:155], v[28:29], v[124:125]
	v_pk_fma_f32 v[126:127], v[156:157], v[30:31], v[126:127]
	v_pk_add_f32 v[124:125], v[124:125], v[126:127]
	v_add_f32_e32 v121, v124, v125
	s_waitcnt vmcnt(13)
	v_cvt_pk_f32_fp8_e32 v[142:143], v108
	v_cvt_pk_f32_fp8_sdwa v[144:145], v108 src0_sel:WORD_1
	v_cvt_pk_f32_fp8_e32 v[146:147], v109
	v_cvt_pk_f32_fp8_sdwa v[148:149], v109 src0_sel:WORD_1
	v_cvt_pk_f32_fp8_e32 v[150:151], v110
	v_cvt_pk_f32_fp8_sdwa v[152:153], v110 src0_sel:WORD_1
	v_cvt_pk_f32_fp8_e32 v[154:155], v111
	v_cvt_pk_f32_fp8_sdwa v[156:157], v111 src0_sel:WORD_1
	v_pk_mul_f32 v[124:125], v[142:143], v[16:17]
	v_pk_mul_f32 v[126:127], v[144:145], v[18:19]
	v_pk_fma_f32 v[124:125], v[146:147], v[20:21], v[124:125]
	v_pk_fma_f32 v[126:127], v[148:149], v[22:23], v[126:127]
	v_pk_fma_f32 v[124:125], v[150:151], v[24:25], v[124:125]
	v_pk_fma_f32 v[126:127], v[152:153], v[26:27], v[126:127]
	v_pk_fma_f32 v[124:125], v[154:155], v[28:29], v[124:125]
	v_pk_fma_f32 v[126:127], v[156:157], v[30:31], v[126:127]
	v_pk_add_f32 v[124:125], v[124:125], v[126:127]
	v_add_f32_e32 v122, v124, v125
	s_waitcnt vmcnt(12)
	v_cvt_pk_f32_fp8_e32 v[142:143], v112
	v_cvt_pk_f32_fp8_sdwa v[144:145], v112 src0_sel:WORD_1
	v_cvt_pk_f32_fp8_e32 v[146:147], v113
	v_cvt_pk_f32_fp8_sdwa v[148:149], v113 src0_sel:WORD_1
	v_cvt_pk_f32_fp8_e32 v[150:151], v114
	v_cvt_pk_f32_fp8_sdwa v[152:153], v114 src0_sel:WORD_1
	v_cvt_pk_f32_fp8_e32 v[154:155], v115
	v_cvt_pk_f32_fp8_sdwa v[156:157], v115 src0_sel:WORD_1
	v_pk_mul_f32 v[124:125], v[142:143], v[16:17]
	v_pk_mul_f32 v[126:127], v[144:145], v[18:19]
	v_pk_fma_f32 v[124:125], v[146:147], v[20:21], v[124:125]
	v_pk_fma_f32 v[126:127], v[148:149], v[22:23], v[126:127]
	v_pk_fma_f32 v[124:125], v[150:151], v[24:25], v[124:125]
	v_pk_fma_f32 v[126:127], v[152:153], v[26:27], v[126:127]
	v_pk_fma_f32 v[124:125], v[154:155], v[28:29], v[124:125]
	v_pk_fma_f32 v[126:127], v[156:157], v[30:31], v[126:127]
	v_pk_add_f32 v[124:125], v[124:125], v[126:127]
	v_add_f32_e32 v123, v124, v125
	v_add_u32_e32 v106, s11, v2
	ds_read_b32 v40, v106 offset:256
	ds_read_b32 v41, v106 offset:288
	ds_read_b32 v42, v106 offset:320
	ds_read_b32 v43, v106 offset:352
	ds_read_b32 v44, v106 offset:384
	ds_read_b32 v45, v106 offset:416
	ds_read_b32 v46, v106 offset:448
	ds_read_b32 v47, v106 offset:480
	s_lshr_b32 s0, s10, 5
	s_and_b32 s1, s10, 31
	s_add_i32 s1, s1, s40
	s_lshl_b32 s0, s0, 21
	s_add_u32 s8, s42, s0
	s_addc_u32 s9, s43, 0
	s_waitcnt lgkmcnt(4)
	v_lshl_add_u32 v40, v40, 7, v1
	global_load_dwordx4 v[80:83], v40, s[8:9]
	v_lshl_add_u32 v41, v41, 7, v1
	global_load_dwordx4 v[84:87], v41, s[8:9]
	v_lshl_add_u32 v42, v42, 7, v1
	global_load_dwordx4 v[88:91], v42, s[8:9]
	v_lshl_add_u32 v43, v43, 7, v1
	global_load_dwordx4 v[92:95], v43, s[8:9]
	s_waitcnt lgkmcnt(0)
	v_lshl_add_u32 v44, v44, 7, v1
	global_load_dwordx4 v[96:99], v44, s[8:9]
	v_lshl_add_u32 v45, v45, 7, v1
	global_load_dwordx4 v[100:103], v45, s[8:9]
	v_lshl_add_u32 v46, v46, 7, v1
	global_load_dwordx4 v[108:111], v46, s[8:9]
	v_lshl_add_u32 v47, v47, 7, v1
	global_load_dwordx4 v[112:115], v47, s[8:9]
	s_nop 1
	v_add_f32_dpp v116, v116, v116 quad_perm:[1,0,3,2] row_mask:0xf bank_mask:0xf
	v_add_f32_dpp v117, v117, v117 quad_perm:[1,0,3,2] row_mask:0xf bank_mask:0xf
	v_add_f32_dpp v118, v118, v118 quad_perm:[1,0,3,2] row_mask:0xf bank_mask:0xf
	v_add_f32_dpp v119, v119, v119 quad_perm:[1,0,3,2] row_mask:0xf bank_mask:0xf
	v_add_f32_dpp v120, v120, v120 quad_perm:[1,0,3,2] row_mask:0xf bank_mask:0xf
	v_add_f32_dpp v121, v121, v121 quad_perm:[1,0,3,2] row_mask:0xf bank_mask:0xf
	v_add_f32_dpp v122, v122, v122 quad_perm:[1,0,3,2] row_mask:0xf bank_mask:0xf
	v_add_f32_dpp v123, v123, v123 quad_perm:[1,0,3,2] row_mask:0xf bank_mask:0xf
	v_add_f32_dpp v116, v116, v116 quad_perm:[2,3,0,1] row_mask:0xf bank_mask:0xf
	v_add_f32_dpp v117, v117, v117 quad_perm:[2,3,0,1] row_mask:0xf bank_mask:0xf
	v_add_f32_dpp v118, v118, v118 quad_perm:[2,3,0,1] row_mask:0xf bank_mask:0xf
	v_add_f32_dpp v119, v119, v119 quad_perm:[2,3,0,1] row_mask:0xf bank_mask:0xf
	v_add_f32_dpp v120, v120, v120 quad_perm:[2,3,0,1] row_mask:0xf bank_mask:0xf
	v_add_f32_dpp v121, v121, v121 quad_perm:[2,3,0,1] row_mask:0xf bank_mask:0xf
	v_add_f32_dpp v122, v122, v122 quad_perm:[2,3,0,1] row_mask:0xf bank_mask:0xf
	v_add_f32_dpp v123, v123, v123 quad_perm:[2,3,0,1] row_mask:0xf bank_mask:0xf
	v_add_f32_dpp v116, v116, v116 row_half_mirror row_mask:0xf bank_mask:0xf
	v_add_f32_dpp v117, v117, v117 row_half_mirror row_mask:0xf bank_mask:0xf
	v_add_f32_dpp v118, v118, v118 row_half_mirror row_mask:0xf bank_mask:0xf
	v_add_f32_dpp v119, v119, v119 row_half_mirror row_mask:0xf bank_mask:0xf
	v_add_f32_dpp v120, v120, v120 row_half_mirror row_mask:0xf bank_mask:0xf
	v_add_f32_dpp v121, v121, v121 row_half_mirror row_mask:0xf bank_mask:0xf
	v_add_f32_dpp v122, v122, v122 row_half_mirror row_mask:0xf bank_mask:0xf
	v_add_f32_dpp v123, v123, v123 row_half_mirror row_mask:0xf bank_mask:0xf
	v_mov_b32_e32 v131, v116
	s_lshl_b64 s[0:1], s[46:47], 1
	v_cndmask_b32_e64 v131, v131, v117, s[0:1]
	s_lshl_b64 s[0:1], s[46:47], 2
	v_cndmask_b32_e64 v131, v131, v118, s[0:1]
	s_lshl_b64 s[0:1], s[46:47], 3
	v_cndmask_b32_e64 v131, v131, v119, s[0:1]
	s_lshl_b64 s[0:1], s[46:47], 4
	v_cndmask_b32_e64 v131, v131, v120, s[0:1]
	s_lshl_b64 s[0:1], s[46:47], 5
	v_cndmask_b32_e64 v131, v131, v121, s[0:1]
	s_lshl_b64 s[0:1], s[46:47], 6
	v_cndmask_b32_e64 v131, v131, v122, s[0:1]
	s_lshl_b64 s[0:1], s[46:47], 7
	v_cndmask_b32_e64 v131, v131, v123, s[0:1]
	s_and_b32 s0, s38, 31
	s_lshl_b32 s0, s0, 9
	v_add_u32_e32 v136, s0, v130
	ds_add_f32 v136, v129
	ds_add_f32 v136, v131 offset:256
	s_waitcnt vmcnt(18)
	v_add_u32_e32 v105, s39, v3
	ds_write_b32 v105, v6
	ds_write_b32 v105, v7 offset:256
	s_add_i32 s10, s38, 3
	s_min_u32 s10, s10, 0xff
	s_lshr_b32 s0, s10, 5
	s_and_b32 s1, s10, 31
	s_add_i32 s1, s1, s40
	s_lshl_b32 s1, s1, 9
	s_add_u32 s12, s6, s1
	s_addc_u32 s13, s7, 0
	global_load_dword v6, v4, s[12:13]
	global_load_dword v7, v4, s[12:13] offset:256
	s_mov_b32 s39, s11
	s_add_i32 s38, s38, 1
	s_cmp_lt_u32 s38, 0x100
	s_cbranch_scc1 .Ldnp_item
	s_waitcnt vmcnt(0)
	v_and_b32_e32 v8, 7, v177
	v_lshrrev_b32_e32 v9, 3, v177
	v_lshl_add_u32 v8, v8, 3, v9
	v_lshlrev_b32_e32 v8, 2, v8
	v_and_b32_e32 v9, 15, v177
	v_lshlrev_b32_e32 v9, 2, v9
	s_mov_b32 s39, 0
